# v68 + odd XCDs sleep ~6.5us at P6 start (pure stagger test)
# speedup vs baseline: 1.0011x; 1.0011x over previous
.LBB0_783:
	s_or_b64 exec, exec, s[0:1]
	s_waitcnt vmcnt(7) lgkmcnt(0)
	v_mov_b32_e32 v0, v210
	s_barrier
	s_bitcmp1_b32 s2, 0
	s_cbranch_scc0 .Lstag6_skip
	s_sleep 127
	s_sleep 127
.Lstag6_skip:
	v_lshl_add_u32 v236, s2, 9, v210
	v_mov_b32_e32 v237, 0
	v_lshlrev_b64 v[236:237], 7, v[236:237]
	s_add_u32 s98, s92, 0x1400000
	s_addc_u32 s99, s93, 0
	v_lshl_add_u64 v[236:237], s[98:99], 0, v[236:237]
	global_load_dword v234, v[236:237], off
	s_mov_b64 s[100:101], 0x1000000
	v_lshl_add_u64 v[236:237], v[236:237], 0, s[100:101]
	global_load_dword v234, v[236:237], off
	s_cmpk_lt_i32 s2, 0x60
	s_cselect_b64 s[0:1], -1, 0
	v_readfirstlane_b32 s4, v0
	s_cmp_lt_u32 s4, 64
	s_cselect_b64 s[4:5], -1, 0
	s_and_b64 s[0:1], s[4:5], s[0:1]
	s_and_b64 vcc, exec, s[0:1]
	s_cbranch_vccz .LBB0_786
	v_mbcnt_hi_u32_b32 v1, -1, v211
	s_waitcnt vmcnt(6)
	v_and_b32_e32 v7, 64, v1
	v_add_u32_e32 v2, -1, v1
	v_cmp_lt_i32_e32 vcc, v2, v7
	v_add_u32_e32 v3, -2, v1
	v_add_u32_e32 v4, -4, v1
	v_cndmask_b32_e32 v2, v2, v1, vcc
	v_cmp_lt_i32_e32 vcc, v3, v7
	v_add_u32_e32 v5, -8, v1
	v_add_u32_e32 v6, -16, v1
	v_cndmask_b32_e32 v3, v3, v1, vcc
	v_cmp_lt_i32_e32 vcc, v4, v7
	s_waitcnt vmcnt(5)
	v_subrev_u32_e32 v8, 32, v1
	s_lshl_b64 s[0:1], s[2:3], 13
	v_cndmask_b32_e32 v4, v4, v1, vcc
	v_cmp_lt_i32_e32 vcc, v5, v7
	v_and_b32_e32 v0, 63, v0
	s_add_u32 s0, s92, s0
	v_cndmask_b32_e32 v5, v5, v1, vcc
	v_cmp_lt_i32_e32 vcc, v6, v7
	v_cmp_gt_u32_e64 s[42:43], 32, v0
	v_cmp_gt_u32_e64 s[44:45], 16, v0
	v_cndmask_b32_e32 v6, v6, v1, vcc
	v_cmp_lt_i32_e32 vcc, v8, v7
	v_cmp_gt_u32_e64 s[46:47], 8, v0
	v_cmp_gt_u32_e64 s[48:49], 4, v0
	v_cndmask_b32_e32 v1, v8, v1, vcc
	v_cmp_gt_u32_e64 s[50:51], 2, v0
	v_cmp_eq_u32_e64 s[52:53], 0, v0
	v_lshlrev_b32_e32 v7, 2, v1
	v_lshlrev_b32_e32 v0, 7, v0
	v_mov_b32_e32 v1, 0
	s_addc_u32 s1, s93, s1
	v_lshl_add_u64 v[0:1], s[0:1], 0, v[0:1]
	s_mov_b64 s[0:1], 0x120000
	v_lshlrev_b32_e32 v2, 2, v2
	v_lshlrev_b32_e32 v3, 2, v3
	v_lshlrev_b32_e32 v4, 2, v4
	v_lshlrev_b32_e32 v5, 2, v5
	v_lshlrev_b32_e32 v6, 2, v6
	v_lshl_add_u64 v[0:1], v[0:1], 0, s[0:1]
	s_lshl_b64 s[0:1], s[94:95], 13
	s_mov_b32 s4, s2
	s_mov_b32 s5, 0xfff31000
